# attn2 V-fragment LDS reads batched; norm_mix phase fast path (4 rows per wave, all loads in flight)
# speedup vs baseline: 1.0638x; 1.0204x over previous
.LBB0_545:
	v_add_u32_e32 v248, v87, v192
	ds_read_b128 v[196:199], v248 offset:9216
	ds_read_b128 v[200:203], v248 offset:9248
	ds_read_b128 v[204:207], v248 offset:11776
	ds_read_b128 v[208:211], v248 offset:14336
	ds_read_b128 v[212:215], v248 offset:16896
	ds_read_b128 v[236:239], v248 offset:11808
	ds_read_b128 v[240:243], v248 offset:14368
	ds_read_b128 v[244:247], v248 offset:16928
	s_nop 1
	v_exp_f32_e32 v2, v70
	v_exp_f32_e32 v71, v71
	v_exp_f32_e32 v72, v72
	v_exp_f32_e32 v73, v73
	v_add_f32_e32 v70, 0, v2
	v_exp_f32_e32 v74, v74
	v_add_f32_e32 v70, v71, v70
	v_exp_f32_e32 v75, v75
	v_add_f32_e32 v70, v72, v70
	v_exp_f32_e32 v76, v76
	v_add_f32_e32 v70, v73, v70
	v_exp_f32_e32 v77, v77
	v_add_f32_e32 v70, v74, v70
	v_exp_f32_e32 v88, v78
	v_add_f32_e32 v70, v75, v70
	v_exp_f32_e32 v89, v79
	v_add_f32_e32 v70, v76, v70
	v_exp_f32_e32 v90, v80
	v_add_f32_e32 v70, v77, v70
	v_exp_f32_e32 v91, v81
	v_add_f32_e32 v70, v88, v70
	v_exp_f32_e32 v82, v82
	v_add_f32_e32 v70, v89, v70
	v_exp_f32_e32 v83, v83
	v_add_f32_e32 v70, v90, v70
	v_exp_f32_e32 v84, v84
	v_add_f32_e32 v70, v91, v70
	v_exp_f32_e32 v85, v85
	v_add_f32_e32 v70, v82, v70
	v_add_f32_e32 v70, v83, v70
	v_add_f32_e32 v70, v84, v70
	v_add_f32_e32 v70, v85, v70
	v_add_f32_e32 v169, v86, v70
	v_cvt_pk_bf16_f32 v70, v2, v71
	v_cvt_pk_bf16_f32 v71, v72, v73
	v_cvt_pk_bf16_f32 v72, v74, v75
	v_cvt_pk_bf16_f32 v73, v76, v77
	s_waitcnt lgkmcnt(7)
	v_mfma_f32_32x32x16_bf16 v[4:19], v[196:199], v[70:73], v[4:19]
	s_add_i32 s17, s16, 1
	s_cmp_lg_u32 s16, 2
	s_cselect_b32 s16, s17, 0
	s_mul_i32 s17, s16, 0x4c00
	v_add_u32_e32 v2, s17, v154
	s_add_i32 s2, s2, 2
	s_waitcnt lgkmcnt(5)
	v_mfma_f32_32x32x16_bf16 v[20:35], v[204:207], v[70:73], v[20:35]
	v_cmp_ge_u32_e32 vcc, s3, v177
	s_or_b64 s[14:15], vcc, s[14:15]
	s_waitcnt lgkmcnt(4)
	v_mfma_f32_32x32x16_bf16 v[38:53], v[208:211], v[70:73], v[38:53]
	s_waitcnt lgkmcnt(3)
	v_mfma_f32_32x32x16_bf16 v[54:69], v[212:215], v[70:73], v[54:69]
	v_cvt_pk_bf16_f32 v70, v88, v89
	v_cvt_pk_bf16_f32 v71, v90, v91
	v_cvt_pk_bf16_f32 v72, v82, v83
	v_cvt_pk_bf16_f32 v73, v84, v85
	s_nop 0
	s_waitcnt lgkmcnt(2)
	v_mfma_f32_32x32x16_bf16 v[20:35], v[236:239], v[70:73], v[20:35]
	s_waitcnt lgkmcnt(1)
	v_mfma_f32_32x32x16_bf16 v[38:53], v[240:243], v[70:73], v[38:53]
	v_mfma_f32_32x32x16_bf16 v[4:19], v[200:203], v[70:73], v[4:19]
	s_waitcnt lgkmcnt(0)
	v_mfma_f32_32x32x16_bf16 v[54:69], v[244:247], v[70:73], v[54:69]
	v_add_u32_e32 v70, v2, v157
	s_waitcnt vmcnt(7)
	ds_write_b128 v70, v[134:137]
	s_waitcnt vmcnt(6)
	ds_write_b128 v70, v[138:141] offset:4608
	v_add_u32_e32 v70, v2, v189
	v_add_u32_e32 v2, v2, v190
	s_waitcnt vmcnt(5)
	ds_write_b128 v70, v[146:149] offset:9216
	s_waitcnt vmcnt(4)
	ds_write_b128 v2, v[142:145] offset:9216
	s_waitcnt lgkmcnt(0)
	s_barrier
	s_andn2_b64 exec, exec, s[14:15]
	s_cbranch_execz .LBB0_550

.LBB0_548:
	v_add_u32_e32 v248, v171, v192
	ds_read_b128 v[196:199], v248 offset:9216
	ds_read_b128 v[200:203], v248 offset:9248
	ds_read_b128 v[204:207], v248 offset:11776
	ds_read_b128 v[208:211], v248 offset:14336
	ds_read_b128 v[212:215], v248 offset:16896
	ds_read_b128 v[236:239], v248 offset:11808
	ds_read_b128 v[240:243], v248 offset:14368
	ds_read_b128 v[244:247], v248 offset:16928
	v_exp_f32_e32 v2, v86
	v_exp_f32_e32 v87, v87
	v_exp_f32_e32 v158, v88
	v_exp_f32_e32 v89, v89
	v_add_f32_e32 v86, 0, v2
	v_exp_f32_e32 v90, v90
	v_add_f32_e32 v86, v87, v86
	v_exp_f32_e32 v91, v91
	v_add_f32_e32 v86, v158, v86
	v_exp_f32_e32 v92, v92
	v_add_f32_e32 v86, v89, v86
	v_exp_f32_e32 v93, v93
	v_add_f32_e32 v86, v90, v86
	v_exp_f32_e32 v159, v94
	v_add_f32_e32 v86, v91, v86
	v_exp_f32_e32 v160, v95
	v_add_f32_e32 v86, v92, v86
	v_exp_f32_e32 v161, v96
	v_add_f32_e32 v86, v93, v86
	v_exp_f32_e32 v173, v97
	v_add_f32_e32 v86, v159, v86
	v_exp_f32_e32 v193, v98
	v_add_f32_e32 v86, v160, v86
	v_exp_f32_e32 v194, v99
	v_add_f32_e32 v86, v161, v86
	v_exp_f32_e32 v100, v100
	v_add_f32_e32 v86, v173, v86
	v_exp_f32_e32 v101, v101
	v_add_f32_e32 v86, v193, v86
	v_add_f32_e32 v86, v194, v86
	v_add_f32_e32 v86, v100, v86
	v_add_f32_e32 v86, v101, v86
	v_add_f32_e32 v86, v169, v86
	v_cvt_pk_bf16_f32 v90, v90, v91
	v_cvt_pk_bf16_f32 v91, v92, v93
	v_cvt_pk_bf16_f32 v88, v2, v87
	v_cvt_pk_bf16_f32 v89, v158, v89
	s_add_i32 s17, s16, 1
	s_cmp_lg_u32 s16, 2
	s_waitcnt lgkmcnt(7)
	v_mfma_f32_32x32x16_bf16 v[4:19], v[196:199], v[88:91], v[4:19]
	s_cselect_b32 s16, s17, 0
	s_mul_i32 s17, s16, 0x4c00
	v_add_u32_e32 v87, s17, v154
	v_add_u32_e32 v2, v87, v157
	v_mov_b32_e32 v71, v70
	v_mov_b32_e32 v72, v70
	s_waitcnt lgkmcnt(5)
	v_mfma_f32_32x32x16_bf16 v[20:35], v[204:207], v[88:91], v[20:35]
	v_mov_b32_e32 v73, v70
	v_mov_b32_e32 v74, v70
	v_mov_b32_e32 v75, v70
	v_mov_b32_e32 v76, v70
	v_mov_b32_e32 v77, v70
	v_mov_b32_e32 v78, v70
	s_waitcnt lgkmcnt(4)
	v_mfma_f32_32x32x16_bf16 v[38:53], v[208:211], v[88:91], v[38:53]
	v_mov_b32_e32 v79, v70
	v_mov_b32_e32 v80, v70
	v_mov_b32_e32 v81, v70
	v_mov_b32_e32 v82, v70
	v_mov_b32_e32 v83, v70
	v_mov_b32_e32 v84, v70
	s_waitcnt lgkmcnt(3)
	v_mfma_f32_32x32x16_bf16 v[54:69], v[212:215], v[88:91], v[54:69]
	v_cvt_pk_bf16_f32 v88, v159, v160
	v_cvt_pk_bf16_f32 v89, v161, v173
	v_cvt_pk_bf16_f32 v90, v193, v194
	v_cvt_pk_bf16_f32 v91, v100, v101
	v_mov_b32_e32 v85, v70
	s_waitcnt lgkmcnt(2)
	v_mfma_f32_32x32x16_bf16 v[20:35], v[236:239], v[88:91], v[20:35]
	s_waitcnt lgkmcnt(1)
	v_mfma_f32_32x32x16_bf16 v[38:53], v[240:243], v[88:91], v[38:53]
	ds_write_b128 v2, v[110:113]
	ds_write_b128 v2, v[122:125] offset:4608
	v_add_u32_e32 v2, v87, v189
	ds_write_b128 v2, v[126:129] offset:9216
	v_add_u32_e32 v2, v87, v190
	ds_write_b128 v2, v[130:133] offset:9216
	v_min_i32_e32 v2, s2, v165
	v_mfma_f32_32x32x16_bf16 v[4:19], v[200:203], v[88:91], v[4:19]
	s_waitcnt lgkmcnt(0)
	s_barrier
	v_mfma_f32_32x32x16_bf16 v[54:69], v[244:247], v[88:91], v[54:69]
	v_lshlrev_b64 v[88:89], 12, v[2:3]
	v_lshl_add_u64 v[90:91], v[180:181], 0, v[88:89]
	v_lshl_add_u64 v[88:89], v[182:183], 0, v[88:89]
	global_load_dwordx4 v[122:125], v[88:89], off
	v_lshlrev_b64 v[88:89], 13, v[2:3]
	global_load_dwordx4 v[110:113], v[90:91], off
	v_lshl_add_u64 v[90:91], v[184:185], 0, v[88:89]
	v_lshl_add_u64 v[88:89], v[186:187], 0, v[88:89]
	global_load_dwordx4 v[126:129], v[90:91], off
	global_load_dwordx4 v[130:133], v[88:89], off
	v_add_u32_e32 v2, v87, v188
	ds_read_b128 v[88:91], v2
	ds_read_b128 v[92:95], v2 offset:32
	s_waitcnt lgkmcnt(1)
	v_mfma_f32_32x32x16_bf16 v[70:85], v[88:91], v[114:117], v[70:85]
	ds_read_b128 v[88:91], v2 offset:64
	s_waitcnt lgkmcnt(1)
	v_mfma_f32_32x32x16_bf16 v[70:85], v[92:95], v[102:105], v[70:85]
	s_waitcnt lgkmcnt(0)
	v_mfma_f32_32x32x16_bf16 v[70:85], v[88:91], v[106:109], v[70:85]
	ds_read_b128 v[88:91], v2 offset:96
	s_waitcnt lgkmcnt(0)
	v_mfma_f32_32x32x16_bf16 v[70:85], v[88:91], v[118:121], v[70:85]
	s_nop 11
	v_max3_f32 v2, v70, s69, v71
	v_max3_f32 v2, v2, v72, v73
	v_max3_f32 v2, v2, v74, v75
	v_max3_f32 v2, v2, v76, v77
	v_max3_f32 v2, v2, v78, v79
	v_max3_f32 v2, v2, v80, v81
	v_max3_f32 v2, v2, v82, v83
	v_max3_f32 v2, v2, v84, v85
	v_cmp_lt_f32_e32 vcc, s22, v2
	s_cbranch_vccz .LBB0_545
	ds_bpermute_b32 v88, v1, v2
	s_waitcnt lgkmcnt(0)
	v_max3_f32 v2, v2, v88, 0
	v_exp_f32_e64 v88, -v2
	v_add_f32_e32 v167, v167, v2
	v_pk_add_f32 v[70:71], v[70:71], v[2:3] op_sel_hi:[1,0] neg_lo:[0,1] neg_hi:[0,1]
	v_pk_add_f32 v[72:73], v[72:73], v[2:3] op_sel_hi:[1,0] neg_lo:[0,1] neg_hi:[0,1]
	v_pk_add_f32 v[74:75], v[74:75], v[2:3] op_sel_hi:[1,0] neg_lo:[0,1] neg_hi:[0,1]
	v_pk_add_f32 v[76:77], v[76:77], v[2:3] op_sel_hi:[1,0] neg_lo:[0,1] neg_hi:[0,1]
	v_pk_add_f32 v[78:79], v[78:79], v[2:3] op_sel_hi:[1,0] neg_lo:[0,1] neg_hi:[0,1]
	v_pk_add_f32 v[80:81], v[80:81], v[2:3] op_sel_hi:[1,0] neg_lo:[0,1] neg_hi:[0,1]
	v_mul_f32_e32 v86, v86, v88
	v_pk_add_f32 v[82:83], v[82:83], v[2:3] op_sel_hi:[1,0] neg_lo:[0,1] neg_hi:[0,1]
	v_pk_add_f32 v[84:85], v[84:85], v[2:3] op_sel_hi:[1,0] neg_lo:[0,1] neg_hi:[0,1]
	v_pk_mul_f32 v[18:19], v[18:19], v[88:89] op_sel_hi:[1,0]
	v_pk_mul_f32 v[16:17], v[16:17], v[88:89] op_sel_hi:[1,0]
	v_pk_mul_f32 v[14:15], v[14:15], v[88:89] op_sel_hi:[1,0]
	v_pk_mul_f32 v[12:13], v[12:13], v[88:89] op_sel_hi:[1,0]
	v_pk_mul_f32 v[10:11], v[10:11], v[88:89] op_sel_hi:[1,0]
	v_pk_mul_f32 v[8:9], v[8:9], v[88:89] op_sel_hi:[1,0]
	v_pk_mul_f32 v[6:7], v[6:7], v[88:89] op_sel_hi:[1,0]
	v_pk_mul_f32 v[4:5], v[4:5], v[88:89] op_sel_hi:[1,0]
	v_pk_mul_f32 v[34:35], v[34:35], v[88:89] op_sel_hi:[1,0]
	v_pk_mul_f32 v[32:33], v[32:33], v[88:89] op_sel_hi:[1,0]
	v_pk_mul_f32 v[30:31], v[30:31], v[88:89] op_sel_hi:[1,0]
	v_pk_mul_f32 v[28:29], v[28:29], v[88:89] op_sel_hi:[1,0]
	v_pk_mul_f32 v[26:27], v[26:27], v[88:89] op_sel_hi:[1,0]
	v_pk_mul_f32 v[24:25], v[24:25], v[88:89] op_sel_hi:[1,0]
	v_pk_mul_f32 v[22:23], v[22:23], v[88:89] op_sel_hi:[1,0]
	v_pk_mul_f32 v[20:21], v[20:21], v[88:89] op_sel_hi:[1,0]
	v_pk_mul_f32 v[52:53], v[52:53], v[88:89] op_sel_hi:[1,0]
	v_pk_mul_f32 v[50:51], v[50:51], v[88:89] op_sel_hi:[1,0]
	v_pk_mul_f32 v[48:49], v[48:49], v[88:89] op_sel_hi:[1,0]
	v_pk_mul_f32 v[46:47], v[46:47], v[88:89] op_sel_hi:[1,0]
	v_pk_mul_f32 v[44:45], v[44:45], v[88:89] op_sel_hi:[1,0]
	v_pk_mul_f32 v[42:43], v[42:43], v[88:89] op_sel_hi:[1,0]
	v_pk_mul_f32 v[40:41], v[40:41], v[88:89] op_sel_hi:[1,0]
	v_pk_mul_f32 v[38:39], v[38:39], v[88:89] op_sel_hi:[1,0]
	v_pk_mul_f32 v[68:69], v[68:69], v[88:89] op_sel_hi:[1,0]
	v_pk_mul_f32 v[66:67], v[66:67], v[88:89] op_sel_hi:[1,0]
	v_pk_mul_f32 v[64:65], v[64:65], v[88:89] op_sel_hi:[1,0]
	v_pk_mul_f32 v[62:63], v[62:63], v[88:89] op_sel_hi:[1,0]
	v_pk_mul_f32 v[60:61], v[60:61], v[88:89] op_sel_hi:[1,0]
	v_pk_mul_f32 v[58:59], v[58:59], v[88:89] op_sel_hi:[1,0]
	v_pk_mul_f32 v[56:57], v[56:57], v[88:89] op_sel_hi:[1,0]
	v_pk_mul_f32 v[54:55], v[54:55], v[88:89] op_sel_hi:[1,0]
	s_branch .LBB0_545

.LBB0_852:
	v_add_u32_e32 v1, s2, v20
	v_mov_b32_e32 v4, 0x2000
	v_cndmask_b32_e64 v1, v4, v1, s[0:1]
	v_cmp_lt_i32_e32 vcc, v20, v1
	s_and_saveexec_b64 s[10:11], vcc
	v_readlane_b32 s3, v254, 7
	s_mul_i32 s2, s3, 3
	s_cbranch_execz .LBB0_869
	s_lshl_b32 s0, s3, 10
	s_ashr_i32 s1, s0, 31
	s_lshl_b64 s[0:1], s[0:1], 2
	s_waitcnt lgkmcnt(0)
	s_add_u32 s0, s4, s0
	s_addc_u32 s1, s5, s1
	s_load_dwordx2 s[14:15], s[30:31], 0x170
	s_load_dwordx4 s[4:7], s[30:31], 0x0
	v_lshlrev_b32_e32 v2, 2, v2
	v_and_b32_e32 v22, 0xfc, v2
	v_lshlrev_b32_e32 v2, 2, v22
	v_and_b32_e32 v4, 64, v223
	v_lshl_add_u64 v[24:25], s[34:35], 0, v[2:3]
	s_waitcnt lgkmcnt(0)
	v_lshl_add_u64 v[26:27], s[14:15], 0, v[2:3]
	v_add_u32_e32 v4, 64, v4
	v_lshl_add_u64 v[28:29], s[0:1], 0, v[2:3]
	v_xor_b32_e32 v2, 32, v223
	v_cmp_lt_i32_e32 vcc, v2, v4
	s_cmp_gt_u32 s26, 11
	v_readlane_b32 s0, v254, 16
	v_cndmask_b32_e32 v2, v223, v2, vcc
	v_lshlrev_b32_e32 v23, 2, v2
	v_xor_b32_e32 v2, 16, v223
	v_cmp_lt_i32_e32 vcc, v2, v4
	v_ashrrev_i32_e32 v21, 31, v20
	s_cselect_b64 s[12:13], -1, 0
	v_cndmask_b32_e32 v2, v223, v2, vcc
	v_lshlrev_b32_e32 v37, 2, v2
	v_xor_b32_e32 v2, 8, v223
	v_cmp_lt_i32_e32 vcc, v2, v4
	v_or_b32_e32 v6, 0x200, v22
	v_or_b32_e32 v8, 0x300, v22
	v_cndmask_b32_e32 v2, v223, v2, vcc
	v_lshlrev_b32_e32 v48, 2, v2
	v_xor_b32_e32 v2, 4, v223
	v_cmp_lt_i32_e32 vcc, v2, v4
	v_readlane_b32 s1, v254, 17
	s_ashr_i32 s9, s8, 31
	v_cndmask_b32_e32 v2, v223, v2, vcc
	v_lshlrev_b32_e32 v49, 2, v2
	v_xor_b32_e32 v2, 2, v223
	v_cmp_lt_i32_e32 vcc, v2, v4
	v_lshlrev_b64 v[10:11], 12, v[20:21]
	v_lshl_add_u64 v[32:33], s[4:5], 0, v[10:11]
	v_cndmask_b32_e32 v2, v223, v2, vcc
	v_lshlrev_b32_e32 v50, 2, v2
	v_xor_b32_e32 v2, 1, v223
	v_cmp_lt_i32_e32 vcc, v2, v4
	v_or_b32_e32 v4, 0x100, v22
	s_lshl_b64 s[4:5], s[8:9], 12
	v_cndmask_b32_e32 v2, v223, v2, vcc
	v_lshlrev_b32_e32 v51, 2, v2
	v_lshlrev_b32_e32 v2, 1, v22
	v_lshl_add_u64 v[30:31], s[0:1], 0, v[2:3]
	s_mov_b64 s[16:17], 0
	v_lshlrev_b32_e32 v34, 2, v4
	v_lshlrev_b32_e32 v38, 2, v6
	v_lshlrev_b32_e32 v40, 2, v8
	v_sub_u32_e32 v4, v1, v20
	s_nop 0
	v_readfirstlane_b32 s0, v4
	s_cmp_eq_u32 s0, 4
	s_cbranch_scc0 .LBB0_855
	s_cmp_eq_u32 s8, 1
	s_cbranch_scc0 .LBB0_855
	v_ashrrev_i32_e32 v43, 31, v20
	v_mov_b32_e32 v42, v20
	s_and_b64 vcc, exec, s[36:37]
	s_cbranch_vccz .Ln0_in
	v_lshlrev_b64 v[4:5], 12, v[42:43]
	v_lshl_add_u64 v[4:5], s[14:15], 0, v[4:5]
	s_branch .Ln0_x
.Ln0_in:
	v_cmp_lt_i32_e64 s[0:1], s27, v20
	v_mov_b64_e32 v[4:5], v[32:33]
	s_and_saveexec_b64 s[18:19], s[0:1]
	v_add_u32_e32 v2, 0xfffff000, v20
	v_lshlrev_b64 v[4:5], 12, v[2:3]
	v_lshl_add_u64 v[4:5], s[6:7], 0, v[4:5]
	s_or_b64 exec, exec, s[18:19]
.Ln0_x:
	v_lshlrev_b32_e32 v2, 2, v22
	v_lshl_add_u64 v[4:5], v[4:5], 0, v[2:3]
	v_lshlrev_b64 v[18:19], 12, v[42:43]
	v_lshl_add_u64 v[6:7], v[24:25], 0, v[18:19]
	v_lshl_add_u64 v[8:9], v[26:27], 0, v[18:19]
	v_cmp_gt_i32_e32 vcc, s67, v20
	s_nop 1
	v_cndmask_b32_e64 v35, 2, 1, vcc
	v_cmp_lt_i32_e32 vcc, s27, v20
	s_nop 1
	v_cndmask_b32_e32 v35, 0, v35, vcc
	v_add_u32_e32 v35, s2, v35
	v_mul_i32_i24_e32 v18, 0x6000, v35
	v_ashrrev_i32_e32 v19, 31, v18
	v_lshl_add_u64 v[10:11], s[40:41], 0, v[18:19]
	v_lshl_add_u64 v[12:13], v[10:11], 0, v[2:3]
	s_mov_b64 s[0:1], 0x1000
	v_lshl_add_u64 v[14:15], v[12:13], 0, s[0:1]
	global_load_dwordx4 v[80:83], v[28:29], off
	global_load_dwordx4 v[84:87], v[28:29], off offset:1024
	global_load_dwordx4 v[88:91], v[28:29], off offset:2048
	global_load_dwordx4 v[92:95], v[28:29], off offset:3072
	global_load_dwordx4 v[96:99], v[12:13], off
	global_load_dwordx4 v[100:103], v[12:13], off offset:1024
	global_load_dwordx4 v[104:107], v[12:13], off offset:2048
	global_load_dwordx4 v[108:111], v[12:13], off offset:3072
	global_load_dwordx4 v[112:115], v[14:15], off
	global_load_dwordx4 v[116:119], v[14:15], off offset:1024
	global_load_dwordx4 v[120:123], v[14:15], off offset:2048
	global_load_dwordx4 v[124:127], v[14:15], off offset:3072
	s_and_b64 vcc, exec, s[12:13]
	s_cbranch_vccnz .Ln0_addp1
	global_load_dwordx4 v[188:191], v[4:5], off
	global_load_dwordx4 v[192:195], v[4:5], off offset:1024
	global_load_dwordx4 v[196:199], v[4:5], off offset:2048
	global_load_dwordx4 v[200:203], v[4:5], off offset:3072
	v_lshl_add_u64 v[4:5], v[4:5], 0, s[4:5]
	global_load_dwordx4 v[204:207], v[4:5], off
	global_load_dwordx4 v[208:211], v[4:5], off offset:1024
	global_load_dwordx4 v[212:215], v[4:5], off offset:2048
	global_load_dwordx4 v[234:237], v[4:5], off offset:3072
	v_lshl_add_u64 v[4:5], v[4:5], 0, s[4:5]
	global_load_dwordx4 v[238:241], v[4:5], off
	global_load_dwordx4 v[242:245], v[4:5], off offset:1024
	global_load_dwordx4 v[246:249], v[4:5], off offset:2048
	global_load_dwordx4 v[250:253], v[4:5], off offset:3072
	v_lshl_add_u64 v[4:5], v[4:5], 0, s[4:5]
	global_load_dwordx4 v[128:131], v[4:5], off
	global_load_dwordx4 v[132:135], v[4:5], off offset:1024
	global_load_dwordx4 v[136:139], v[4:5], off offset:2048
	global_load_dwordx4 v[142:145], v[4:5], off offset:3072
	s_waitcnt vmcnt(0)
	v_pk_mul_f32 v[18:19], v[188:189], v[188:189]
	v_pk_mul_f32 v[170:171], v[190:191], v[190:191]
	v_add_f32_e32 v44, v19, v18
	v_add_f32_e32 v44, v170, v44
	v_add_f32_e32 v44, v171, v44
	v_pk_mul_f32 v[18:19], v[192:193], v[192:193]
	v_pk_mul_f32 v[170:171], v[194:195], v[194:195]
	v_add_f32_e32 v45, v19, v18
	v_add_f32_e32 v45, v170, v45
	v_add_f32_e32 v45, v171, v45
	v_pk_mul_f32 v[18:19], v[196:197], v[196:197]
	v_pk_mul_f32 v[170:171], v[198:199], v[198:199]
	v_add_f32_e32 v46, v19, v18
	v_add_f32_e32 v46, v170, v46
	v_add_f32_e32 v46, v171, v46
	v_pk_mul_f32 v[18:19], v[200:201], v[200:201]
	v_pk_mul_f32 v[170:171], v[202:203], v[202:203]
	v_add_f32_e32 v47, v19, v18
	v_add_f32_e32 v47, v170, v47
	v_add_f32_e32 v47, v171, v47
	v_add_f32_e32 v158, v44, v45
	v_add_f32_e32 v158, v158, v46
	v_add_f32_e32 v158, v158, v47
	v_pk_mul_f32 v[18:19], v[204:205], v[204:205]
	v_pk_mul_f32 v[170:171], v[206:207], v[206:207]
	v_add_f32_e32 v44, v19, v18
	v_add_f32_e32 v44, v170, v44
	v_add_f32_e32 v44, v171, v44
	v_pk_mul_f32 v[18:19], v[208:209], v[208:209]
	v_pk_mul_f32 v[170:171], v[210:211], v[210:211]
	v_add_f32_e32 v45, v19, v18
	v_add_f32_e32 v45, v170, v45
	v_add_f32_e32 v45, v171, v45
	v_pk_mul_f32 v[18:19], v[212:213], v[212:213]
	v_pk_mul_f32 v[170:171], v[214:215], v[214:215]
	v_add_f32_e32 v46, v19, v18
	v_add_f32_e32 v46, v170, v46
	v_add_f32_e32 v46, v171, v46
	v_pk_mul_f32 v[18:19], v[234:235], v[234:235]
	v_pk_mul_f32 v[170:171], v[236:237], v[236:237]
	v_add_f32_e32 v47, v19, v18
	v_add_f32_e32 v47, v170, v47
	v_add_f32_e32 v47, v171, v47
	v_add_f32_e32 v160, v44, v45
	v_add_f32_e32 v160, v160, v46
	v_add_f32_e32 v160, v160, v47
	v_pk_mul_f32 v[18:19], v[238:239], v[238:239]
	v_pk_mul_f32 v[170:171], v[240:241], v[240:241]
	v_add_f32_e32 v44, v19, v18
	v_add_f32_e32 v44, v170, v44
	v_add_f32_e32 v44, v171, v44
	v_pk_mul_f32 v[18:19], v[242:243], v[242:243]
	v_pk_mul_f32 v[170:171], v[244:245], v[244:245]
	v_add_f32_e32 v45, v19, v18
	v_add_f32_e32 v45, v170, v45
	v_add_f32_e32 v45, v171, v45
	v_pk_mul_f32 v[18:19], v[246:247], v[246:247]
	v_pk_mul_f32 v[170:171], v[248:249], v[248:249]
	v_add_f32_e32 v46, v19, v18
	v_add_f32_e32 v46, v170, v46
	v_add_f32_e32 v46, v171, v46
	v_pk_mul_f32 v[18:19], v[250:251], v[250:251]
	v_pk_mul_f32 v[170:171], v[252:253], v[252:253]
	v_add_f32_e32 v47, v19, v18
	v_add_f32_e32 v47, v170, v47
	v_add_f32_e32 v47, v171, v47
	v_add_f32_e32 v162, v44, v45
	v_add_f32_e32 v162, v162, v46
	v_add_f32_e32 v162, v162, v47
	v_pk_mul_f32 v[18:19], v[128:129], v[128:129]
	v_pk_mul_f32 v[170:171], v[130:131], v[130:131]
	v_add_f32_e32 v44, v19, v18
	v_add_f32_e32 v44, v170, v44
	v_add_f32_e32 v44, v171, v44
	v_pk_mul_f32 v[18:19], v[132:133], v[132:133]
	v_pk_mul_f32 v[170:171], v[134:135], v[134:135]
	v_add_f32_e32 v45, v19, v18
	v_add_f32_e32 v45, v170, v45
	v_add_f32_e32 v45, v171, v45
	v_pk_mul_f32 v[18:19], v[136:137], v[136:137]
	v_pk_mul_f32 v[170:171], v[138:139], v[138:139]
	v_add_f32_e32 v46, v19, v18
	v_add_f32_e32 v46, v170, v46
	v_add_f32_e32 v46, v171, v46
	v_pk_mul_f32 v[18:19], v[142:143], v[142:143]
	v_pk_mul_f32 v[170:171], v[144:145], v[144:145]
	v_add_f32_e32 v47, v19, v18
	v_add_f32_e32 v47, v170, v47
	v_add_f32_e32 v47, v171, v47
	v_add_f32_e32 v164, v44, v45
	v_add_f32_e32 v164, v164, v46
	v_add_f32_e32 v164, v164, v47
	ds_bpermute_b32 v166, v23, v158
	ds_bpermute_b32 v167, v23, v160
	ds_bpermute_b32 v168, v23, v162
	ds_bpermute_b32 v169, v23, v164
	s_waitcnt lgkmcnt(3)
	v_add_f32_e32 v158, v158, v166
	s_waitcnt lgkmcnt(2)
	v_add_f32_e32 v160, v160, v167
	s_waitcnt lgkmcnt(1)
	v_add_f32_e32 v162, v162, v168
	s_waitcnt lgkmcnt(0)
	v_add_f32_e32 v164, v164, v169
	ds_bpermute_b32 v166, v37, v158
	ds_bpermute_b32 v167, v37, v160
	ds_bpermute_b32 v168, v37, v162
	ds_bpermute_b32 v169, v37, v164
	s_waitcnt lgkmcnt(3)
	v_add_f32_e32 v158, v158, v166
	s_waitcnt lgkmcnt(2)
	v_add_f32_e32 v160, v160, v167
	s_waitcnt lgkmcnt(1)
	v_add_f32_e32 v162, v162, v168
	s_waitcnt lgkmcnt(0)
	v_add_f32_e32 v164, v164, v169
	ds_bpermute_b32 v166, v48, v158
	ds_bpermute_b32 v167, v48, v160
	ds_bpermute_b32 v168, v48, v162
	ds_bpermute_b32 v169, v48, v164
	s_waitcnt lgkmcnt(3)
	v_add_f32_e32 v158, v158, v166
	s_waitcnt lgkmcnt(2)
	v_add_f32_e32 v160, v160, v167
	s_waitcnt lgkmcnt(1)
	v_add_f32_e32 v162, v162, v168
	s_waitcnt lgkmcnt(0)
	v_add_f32_e32 v164, v164, v169
	ds_bpermute_b32 v166, v49, v158
	ds_bpermute_b32 v167, v49, v160
	ds_bpermute_b32 v168, v49, v162
	ds_bpermute_b32 v169, v49, v164
	s_waitcnt lgkmcnt(3)
	v_add_f32_e32 v158, v158, v166
	s_waitcnt lgkmcnt(2)
	v_add_f32_e32 v160, v160, v167
	s_waitcnt lgkmcnt(1)
	v_add_f32_e32 v162, v162, v168
	s_waitcnt lgkmcnt(0)
	v_add_f32_e32 v164, v164, v169
	ds_bpermute_b32 v166, v50, v158
	ds_bpermute_b32 v167, v50, v160
	ds_bpermute_b32 v168, v50, v162
	ds_bpermute_b32 v169, v50, v164
	s_waitcnt lgkmcnt(3)
	v_add_f32_e32 v158, v158, v166
	s_waitcnt lgkmcnt(2)
	v_add_f32_e32 v160, v160, v167
	s_waitcnt lgkmcnt(1)
	v_add_f32_e32 v162, v162, v168
	s_waitcnt lgkmcnt(0)
	v_add_f32_e32 v164, v164, v169
	ds_bpermute_b32 v166, v51, v158
	ds_bpermute_b32 v167, v51, v160
	ds_bpermute_b32 v168, v51, v162
	ds_bpermute_b32 v169, v51, v164
	s_waitcnt lgkmcnt(3)
	v_add_f32_e32 v158, v158, v166
	s_waitcnt lgkmcnt(2)
	v_add_f32_e32 v160, v160, v167
	s_waitcnt lgkmcnt(1)
	v_add_f32_e32 v162, v162, v168
	s_waitcnt lgkmcnt(0)
	v_add_f32_e32 v164, v164, v169
	v_pk_add_f32 v[112:113], v[112:113], 1.0 op_sel_hi:[1,0]
	v_pk_add_f32 v[114:115], v[114:115], 1.0 op_sel_hi:[1,0]
	v_pk_add_f32 v[116:117], v[116:117], 1.0 op_sel_hi:[1,0]
	v_pk_add_f32 v[118:119], v[118:119], 1.0 op_sel_hi:[1,0]
	v_pk_add_f32 v[120:121], v[120:121], 1.0 op_sel_hi:[1,0]
	v_pk_add_f32 v[122:123], v[122:123], 1.0 op_sel_hi:[1,0]
	v_pk_add_f32 v[124:125], v[124:125], 1.0 op_sel_hi:[1,0]
	v_pk_add_f32 v[126:127], v[126:127], 1.0 op_sel_hi:[1,0]
	v_fmamk_f32 v158, v158, 0x3a800000, v218
	v_mul_f32_e32 v170, 0x4b800000, v158
	v_cmp_gt_f32_e32 vcc, s71, v158
	s_nop 1
	v_cndmask_b32_e32 v158, v158, v170, vcc
	v_rsq_f32_e32 v158, v158
	s_nop 0
	v_mul_f32_e32 v170, 0x45800000, v158
	v_cndmask_b32_e32 v158, v158, v170, vcc
	v_fmamk_f32 v160, v160, 0x3a800000, v218
	v_mul_f32_e32 v170, 0x4b800000, v160
	v_cmp_gt_f32_e32 vcc, s71, v160
	s_nop 1
	v_cndmask_b32_e32 v160, v160, v170, vcc
	v_rsq_f32_e32 v160, v160
	s_nop 0
	v_mul_f32_e32 v170, 0x45800000, v160
	v_cndmask_b32_e32 v160, v160, v170, vcc
	v_fmamk_f32 v162, v162, 0x3a800000, v218
	v_mul_f32_e32 v170, 0x4b800000, v162
	v_cmp_gt_f32_e32 vcc, s71, v162
	s_nop 1
	v_cndmask_b32_e32 v162, v162, v170, vcc
	v_rsq_f32_e32 v162, v162
	s_nop 0
	v_mul_f32_e32 v170, 0x45800000, v162
	v_cndmask_b32_e32 v162, v162, v170, vcc
	v_fmamk_f32 v164, v164, 0x3a800000, v218
	v_mul_f32_e32 v170, 0x4b800000, v164
	v_cmp_gt_f32_e32 vcc, s71, v164
	s_nop 1
	v_cndmask_b32_e32 v164, v164, v170, vcc
	v_rsq_f32_e32 v164, v164
	s_nop 0
	v_mul_f32_e32 v170, 0x45800000, v164
	v_cndmask_b32_e32 v164, v164, v170, vcc
	s_mov_b64 s[18:19], 0x800
	v_lshlrev_b64 v[16:17], 11, v[42:43]
	v_lshl_add_u64 v[16:17], v[30:31], 0, v[16:17]
	v_pk_mul_f32 v[188:189], v[188:189], v[158:159] op_sel_hi:[1,0]
	v_pk_mul_f32 v[188:189], v[80:81], v[188:189]
	v_pk_fma_f32 v[188:189], v[112:113], v[188:189], v[96:97]
	v_pk_mul_f32 v[190:191], v[190:191], v[158:159] op_sel_hi:[1,0]
	v_pk_mul_f32 v[190:191], v[82:83], v[190:191]
	v_pk_fma_f32 v[190:191], v[114:115], v[190:191], v[98:99]
	v_cvt_pk_bf16_f32 v188, v188, v189
	v_cvt_pk_bf16_f32 v189, v190, v191
	global_store_dwordx2 v[16:17], v[188:189], off
	v_pk_mul_f32 v[192:193], v[192:193], v[158:159] op_sel_hi:[1,0]
	v_pk_mul_f32 v[192:193], v[84:85], v[192:193]
	v_pk_fma_f32 v[192:193], v[116:117], v[192:193], v[100:101]
	v_pk_mul_f32 v[194:195], v[194:195], v[158:159] op_sel_hi:[1,0]
	v_pk_mul_f32 v[194:195], v[86:87], v[194:195]
	v_pk_fma_f32 v[194:195], v[118:119], v[194:195], v[102:103]
	v_cvt_pk_bf16_f32 v192, v192, v193
	v_cvt_pk_bf16_f32 v193, v194, v195
	global_store_dwordx2 v[16:17], v[192:193], off offset:512
	v_pk_mul_f32 v[196:197], v[196:197], v[158:159] op_sel_hi:[1,0]
	v_pk_mul_f32 v[196:197], v[88:89], v[196:197]
	v_pk_fma_f32 v[196:197], v[120:121], v[196:197], v[104:105]
	v_pk_mul_f32 v[198:199], v[198:199], v[158:159] op_sel_hi:[1,0]
	v_pk_mul_f32 v[198:199], v[90:91], v[198:199]
	v_pk_fma_f32 v[198:199], v[122:123], v[198:199], v[106:107]
	v_cvt_pk_bf16_f32 v196, v196, v197
	v_cvt_pk_bf16_f32 v197, v198, v199
	global_store_dwordx2 v[16:17], v[196:197], off offset:1024
	v_pk_mul_f32 v[200:201], v[200:201], v[158:159] op_sel_hi:[1,0]
	v_pk_mul_f32 v[200:201], v[92:93], v[200:201]
	v_pk_fma_f32 v[200:201], v[124:125], v[200:201], v[108:109]
	v_pk_mul_f32 v[202:203], v[202:203], v[158:159] op_sel_hi:[1,0]
	v_pk_mul_f32 v[202:203], v[94:95], v[202:203]
	v_pk_fma_f32 v[202:203], v[126:127], v[202:203], v[110:111]
	v_cvt_pk_bf16_f32 v200, v200, v201
	v_cvt_pk_bf16_f32 v201, v202, v203
	global_store_dwordx2 v[16:17], v[200:201], off offset:1536
	v_lshl_add_u64 v[16:17], v[16:17], 0, s[18:19]
	v_pk_mul_f32 v[204:205], v[204:205], v[160:161] op_sel_hi:[1,0]
	v_pk_mul_f32 v[204:205], v[80:81], v[204:205]
	v_pk_fma_f32 v[204:205], v[112:113], v[204:205], v[96:97]
	v_pk_mul_f32 v[206:207], v[206:207], v[160:161] op_sel_hi:[1,0]
	v_pk_mul_f32 v[206:207], v[82:83], v[206:207]
	v_pk_fma_f32 v[206:207], v[114:115], v[206:207], v[98:99]
	v_cvt_pk_bf16_f32 v204, v204, v205
	v_cvt_pk_bf16_f32 v205, v206, v207
	global_store_dwordx2 v[16:17], v[204:205], off
	v_pk_mul_f32 v[208:209], v[208:209], v[160:161] op_sel_hi:[1,0]
	v_pk_mul_f32 v[208:209], v[84:85], v[208:209]
	v_pk_fma_f32 v[208:209], v[116:117], v[208:209], v[100:101]
	v_pk_mul_f32 v[210:211], v[210:211], v[160:161] op_sel_hi:[1,0]
	v_pk_mul_f32 v[210:211], v[86:87], v[210:211]
	v_pk_fma_f32 v[210:211], v[118:119], v[210:211], v[102:103]
	v_cvt_pk_bf16_f32 v208, v208, v209
	v_cvt_pk_bf16_f32 v209, v210, v211
	global_store_dwordx2 v[16:17], v[208:209], off offset:512
	v_pk_mul_f32 v[212:213], v[212:213], v[160:161] op_sel_hi:[1,0]
	v_pk_mul_f32 v[212:213], v[88:89], v[212:213]
	v_pk_fma_f32 v[212:213], v[120:121], v[212:213], v[104:105]
	v_pk_mul_f32 v[214:215], v[214:215], v[160:161] op_sel_hi:[1,0]
	v_pk_mul_f32 v[214:215], v[90:91], v[214:215]
	v_pk_fma_f32 v[214:215], v[122:123], v[214:215], v[106:107]
	v_cvt_pk_bf16_f32 v212, v212, v213
	v_cvt_pk_bf16_f32 v213, v214, v215
	global_store_dwordx2 v[16:17], v[212:213], off offset:1024
	v_pk_mul_f32 v[234:235], v[234:235], v[160:161] op_sel_hi:[1,0]
	v_pk_mul_f32 v[234:235], v[92:93], v[234:235]
	v_pk_fma_f32 v[234:235], v[124:125], v[234:235], v[108:109]
	v_pk_mul_f32 v[236:237], v[236:237], v[160:161] op_sel_hi:[1,0]
	v_pk_mul_f32 v[236:237], v[94:95], v[236:237]
	v_pk_fma_f32 v[236:237], v[126:127], v[236:237], v[110:111]
	v_cvt_pk_bf16_f32 v234, v234, v235
	v_cvt_pk_bf16_f32 v235, v236, v237
	global_store_dwordx2 v[16:17], v[234:235], off offset:1536
	v_lshl_add_u64 v[16:17], v[16:17], 0, s[18:19]
	v_pk_mul_f32 v[238:239], v[238:239], v[162:163] op_sel_hi:[1,0]
	v_pk_mul_f32 v[238:239], v[80:81], v[238:239]
	v_pk_fma_f32 v[238:239], v[112:113], v[238:239], v[96:97]
	v_pk_mul_f32 v[240:241], v[240:241], v[162:163] op_sel_hi:[1,0]
	v_pk_mul_f32 v[240:241], v[82:83], v[240:241]
	v_pk_fma_f32 v[240:241], v[114:115], v[240:241], v[98:99]
	v_cvt_pk_bf16_f32 v238, v238, v239
	v_cvt_pk_bf16_f32 v239, v240, v241
	global_store_dwordx2 v[16:17], v[238:239], off
	v_pk_mul_f32 v[242:243], v[242:243], v[162:163] op_sel_hi:[1,0]
	v_pk_mul_f32 v[242:243], v[84:85], v[242:243]
	v_pk_fma_f32 v[242:243], v[116:117], v[242:243], v[100:101]
	v_pk_mul_f32 v[244:245], v[244:245], v[162:163] op_sel_hi:[1,0]
	v_pk_mul_f32 v[244:245], v[86:87], v[244:245]
	v_pk_fma_f32 v[244:245], v[118:119], v[244:245], v[102:103]
	v_cvt_pk_bf16_f32 v242, v242, v243
	v_cvt_pk_bf16_f32 v243, v244, v245
	global_store_dwordx2 v[16:17], v[242:243], off offset:512
	v_pk_mul_f32 v[246:247], v[246:247], v[162:163] op_sel_hi:[1,0]
	v_pk_mul_f32 v[246:247], v[88:89], v[246:247]
	v_pk_fma_f32 v[246:247], v[120:121], v[246:247], v[104:105]
	v_pk_mul_f32 v[248:249], v[248:249], v[162:163] op_sel_hi:[1,0]
	v_pk_mul_f32 v[248:249], v[90:91], v[248:249]
	v_pk_fma_f32 v[248:249], v[122:123], v[248:249], v[106:107]
	v_cvt_pk_bf16_f32 v246, v246, v247
	v_cvt_pk_bf16_f32 v247, v248, v249
	global_store_dwordx2 v[16:17], v[246:247], off offset:1024
	v_pk_mul_f32 v[250:251], v[250:251], v[162:163] op_sel_hi:[1,0]
	v_pk_mul_f32 v[250:251], v[92:93], v[250:251]
	v_pk_fma_f32 v[250:251], v[124:125], v[250:251], v[108:109]
	v_pk_mul_f32 v[252:253], v[252:253], v[162:163] op_sel_hi:[1,0]
	v_pk_mul_f32 v[252:253], v[94:95], v[252:253]
	v_pk_fma_f32 v[252:253], v[126:127], v[252:253], v[110:111]
	v_cvt_pk_bf16_f32 v250, v250, v251
	v_cvt_pk_bf16_f32 v251, v252, v253
	global_store_dwordx2 v[16:17], v[250:251], off offset:1536
	v_lshl_add_u64 v[16:17], v[16:17], 0, s[18:19]
	v_pk_mul_f32 v[128:129], v[128:129], v[164:165] op_sel_hi:[1,0]
	v_pk_mul_f32 v[128:129], v[80:81], v[128:129]
	v_pk_fma_f32 v[128:129], v[112:113], v[128:129], v[96:97]
	v_pk_mul_f32 v[130:131], v[130:131], v[164:165] op_sel_hi:[1,0]
	v_pk_mul_f32 v[130:131], v[82:83], v[130:131]
	v_pk_fma_f32 v[130:131], v[114:115], v[130:131], v[98:99]
	v_cvt_pk_bf16_f32 v128, v128, v129
	v_cvt_pk_bf16_f32 v129, v130, v131
	global_store_dwordx2 v[16:17], v[128:129], off
	v_pk_mul_f32 v[132:133], v[132:133], v[164:165] op_sel_hi:[1,0]
	v_pk_mul_f32 v[132:133], v[84:85], v[132:133]
	v_pk_fma_f32 v[132:133], v[116:117], v[132:133], v[100:101]
	v_pk_mul_f32 v[134:135], v[134:135], v[164:165] op_sel_hi:[1,0]
	v_pk_mul_f32 v[134:135], v[86:87], v[134:135]
	v_pk_fma_f32 v[134:135], v[118:119], v[134:135], v[102:103]
	v_cvt_pk_bf16_f32 v132, v132, v133
	v_cvt_pk_bf16_f32 v133, v134, v135
	global_store_dwordx2 v[16:17], v[132:133], off offset:512
	v_pk_mul_f32 v[136:137], v[136:137], v[164:165] op_sel_hi:[1,0]
	v_pk_mul_f32 v[136:137], v[88:89], v[136:137]
	v_pk_fma_f32 v[136:137], v[120:121], v[136:137], v[104:105]
	v_pk_mul_f32 v[138:139], v[138:139], v[164:165] op_sel_hi:[1,0]
	v_pk_mul_f32 v[138:139], v[90:91], v[138:139]
	v_pk_fma_f32 v[138:139], v[122:123], v[138:139], v[106:107]
	v_cvt_pk_bf16_f32 v136, v136, v137
	v_cvt_pk_bf16_f32 v137, v138, v139
	global_store_dwordx2 v[16:17], v[136:137], off offset:1024
	v_pk_mul_f32 v[142:143], v[142:143], v[164:165] op_sel_hi:[1,0]
	v_pk_mul_f32 v[142:143], v[92:93], v[142:143]
	v_pk_fma_f32 v[142:143], v[124:125], v[142:143], v[108:109]
	v_pk_mul_f32 v[144:145], v[144:145], v[164:165] op_sel_hi:[1,0]
	v_pk_mul_f32 v[144:145], v[94:95], v[144:145]
	v_pk_fma_f32 v[144:145], v[126:127], v[144:145], v[110:111]
	v_cvt_pk_bf16_f32 v142, v142, v143
	v_cvt_pk_bf16_f32 v143, v144, v145
	global_store_dwordx2 v[16:17], v[142:143], off offset:1536
	s_branch .LBB0_869
.Ln0_addp1:
	global_load_dwordx4 v[188:191], v[4:5], off
	global_load_dwordx4 v[192:195], v[4:5], off offset:1024
	global_load_dwordx4 v[196:199], v[4:5], off offset:2048
	global_load_dwordx4 v[200:203], v[4:5], off offset:3072
	global_load_dwordx4 v[52:55], v[6:7], off
	global_load_dwordx4 v[56:59], v[6:7], off offset:1024
	global_load_dwordx4 v[60:63], v[6:7], off offset:2048
	global_load_dwordx4 v[64:67], v[6:7], off offset:3072
	v_lshl_add_u64 v[4:5], v[4:5], 0, s[4:5]
	global_load_dwordx4 v[204:207], v[4:5], off
	global_load_dwordx4 v[208:211], v[4:5], off offset:1024
	global_load_dwordx4 v[212:215], v[4:5], off offset:2048
	global_load_dwordx4 v[234:237], v[4:5], off offset:3072
	v_lshl_add_u64 v[6:7], v[6:7], 0, s[4:5]
	global_load_dwordx4 v[68:71], v[6:7], off
	global_load_dwordx4 v[72:75], v[6:7], off offset:1024
	global_load_dwordx4 v[76:79], v[6:7], off offset:2048
	global_load_dwordx4 v[146:149], v[6:7], off offset:3072
	v_lshl_add_u64 v[4:5], v[4:5], 0, s[4:5]
	global_load_dwordx4 v[238:241], v[4:5], off
	global_load_dwordx4 v[242:245], v[4:5], off offset:1024
	global_load_dwordx4 v[246:249], v[4:5], off offset:2048
	global_load_dwordx4 v[250:253], v[4:5], off offset:3072
	v_lshl_add_u64 v[4:5], v[4:5], 0, s[4:5]
	global_load_dwordx4 v[128:131], v[4:5], off
	global_load_dwordx4 v[132:135], v[4:5], off offset:1024
	global_load_dwordx4 v[136:139], v[4:5], off offset:2048
	global_load_dwordx4 v[142:145], v[4:5], off offset:3072
	s_waitcnt vmcnt(20)
	s_waitcnt vmcnt(19)
	v_pk_add_f32 v[188:189], v[188:189], v[52:53]
	v_pk_add_f32 v[190:191], v[190:191], v[54:55]
	global_store_dwordx4 v[8:9], v[188:191], off
	s_waitcnt vmcnt(19)
	v_pk_add_f32 v[192:193], v[192:193], v[56:57]
	v_pk_add_f32 v[194:195], v[194:195], v[58:59]
	global_store_dwordx4 v[8:9], v[192:195], off offset:1024
	s_waitcnt vmcnt(19)
	v_pk_add_f32 v[196:197], v[196:197], v[60:61]
	v_pk_add_f32 v[198:199], v[198:199], v[62:63]
	global_store_dwordx4 v[8:9], v[196:199], off offset:2048
	s_waitcnt vmcnt(19)
	v_pk_add_f32 v[200:201], v[200:201], v[64:65]
	v_pk_add_f32 v[202:203], v[202:203], v[66:67]
	global_store_dwordx4 v[8:9], v[200:203], off offset:3072
	v_lshl_add_u64 v[6:7], v[6:7], 0, s[4:5]
	global_load_dwordx4 v[52:55], v[6:7], off
	global_load_dwordx4 v[56:59], v[6:7], off offset:1024
	global_load_dwordx4 v[60:63], v[6:7], off offset:2048
	global_load_dwordx4 v[64:67], v[6:7], off offset:3072
	v_lshl_add_u64 v[8:9], v[8:9], 0, s[4:5]
	s_waitcnt vmcnt(20)
	s_waitcnt vmcnt(19)
	v_pk_add_f32 v[204:205], v[204:205], v[68:69]
	v_pk_add_f32 v[206:207], v[206:207], v[70:71]
	global_store_dwordx4 v[8:9], v[204:207], off
	s_waitcnt vmcnt(19)
	v_pk_add_f32 v[208:209], v[208:209], v[72:73]
	v_pk_add_f32 v[210:211], v[210:211], v[74:75]
	global_store_dwordx4 v[8:9], v[208:211], off offset:1024
	s_waitcnt vmcnt(19)
	v_pk_add_f32 v[212:213], v[212:213], v[76:77]
	v_pk_add_f32 v[214:215], v[214:215], v[78:79]
	global_store_dwordx4 v[8:9], v[212:215], off offset:2048
	s_waitcnt vmcnt(19)
	v_pk_add_f32 v[234:235], v[234:235], v[146:147]
	v_pk_add_f32 v[236:237], v[236:237], v[148:149]
	global_store_dwordx4 v[8:9], v[234:237], off offset:3072
	v_lshl_add_u64 v[6:7], v[6:7], 0, s[4:5]
	global_load_dwordx4 v[68:71], v[6:7], off
	global_load_dwordx4 v[72:75], v[6:7], off offset:1024
	global_load_dwordx4 v[76:79], v[6:7], off offset:2048
	global_load_dwordx4 v[146:149], v[6:7], off offset:3072
	v_lshl_add_u64 v[8:9], v[8:9], 0, s[4:5]
	s_waitcnt vmcnt(20)
	s_waitcnt vmcnt(11)
	v_pk_add_f32 v[238:239], v[238:239], v[52:53]
	v_pk_add_f32 v[240:241], v[240:241], v[54:55]
	global_store_dwordx4 v[8:9], v[238:241], off
	s_waitcnt vmcnt(11)
	v_pk_add_f32 v[242:243], v[242:243], v[56:57]
	v_pk_add_f32 v[244:245], v[244:245], v[58:59]
	global_store_dwordx4 v[8:9], v[242:245], off offset:1024
	s_waitcnt vmcnt(11)
	v_pk_add_f32 v[246:247], v[246:247], v[60:61]
	v_pk_add_f32 v[248:249], v[248:249], v[62:63]
	global_store_dwordx4 v[8:9], v[246:249], off offset:2048
	s_waitcnt vmcnt(11)
	v_pk_add_f32 v[250:251], v[250:251], v[64:65]
	v_pk_add_f32 v[252:253], v[252:253], v[66:67]
	global_store_dwordx4 v[8:9], v[250:253], off offset:3072
	v_lshl_add_u64 v[8:9], v[8:9], 0, s[4:5]
	s_waitcnt vmcnt(20)
	s_waitcnt vmcnt(7)
	v_pk_add_f32 v[128:129], v[128:129], v[68:69]
	v_pk_add_f32 v[130:131], v[130:131], v[70:71]
	global_store_dwordx4 v[8:9], v[128:131], off
	s_waitcnt vmcnt(7)
	v_pk_add_f32 v[132:133], v[132:133], v[72:73]
	v_pk_add_f32 v[134:135], v[134:135], v[74:75]
	global_store_dwordx4 v[8:9], v[132:135], off offset:1024
	s_waitcnt vmcnt(7)
	v_pk_add_f32 v[136:137], v[136:137], v[76:77]
	v_pk_add_f32 v[138:139], v[138:139], v[78:79]
	global_store_dwordx4 v[8:9], v[136:139], off offset:2048
	s_waitcnt vmcnt(7)
	v_pk_add_f32 v[142:143], v[142:143], v[146:147]
	v_pk_add_f32 v[144:145], v[144:145], v[148:149]
	global_store_dwordx4 v[8:9], v[142:145], off offset:3072
	v_pk_mul_f32 v[18:19], v[188:189], v[188:189]
	v_pk_mul_f32 v[170:171], v[190:191], v[190:191]
	v_add_f32_e32 v44, v19, v18
	v_add_f32_e32 v44, v170, v44
	v_add_f32_e32 v44, v171, v44
	v_pk_mul_f32 v[18:19], v[192:193], v[192:193]
	v_pk_mul_f32 v[170:171], v[194:195], v[194:195]
	v_add_f32_e32 v45, v19, v18
	v_add_f32_e32 v45, v170, v45
	v_add_f32_e32 v45, v171, v45
	v_pk_mul_f32 v[18:19], v[196:197], v[196:197]
	v_pk_mul_f32 v[170:171], v[198:199], v[198:199]
	v_add_f32_e32 v46, v19, v18
	v_add_f32_e32 v46, v170, v46
	v_add_f32_e32 v46, v171, v46
	v_pk_mul_f32 v[18:19], v[200:201], v[200:201]
	v_pk_mul_f32 v[170:171], v[202:203], v[202:203]
	v_add_f32_e32 v47, v19, v18
	v_add_f32_e32 v47, v170, v47
	v_add_f32_e32 v47, v171, v47
	v_add_f32_e32 v158, v44, v45
	v_add_f32_e32 v158, v158, v46
	v_add_f32_e32 v158, v158, v47
	v_pk_mul_f32 v[18:19], v[204:205], v[204:205]
	v_pk_mul_f32 v[170:171], v[206:207], v[206:207]
	v_add_f32_e32 v44, v19, v18
	v_add_f32_e32 v44, v170, v44
	v_add_f32_e32 v44, v171, v44
	v_pk_mul_f32 v[18:19], v[208:209], v[208:209]
	v_pk_mul_f32 v[170:171], v[210:211], v[210:211]
	v_add_f32_e32 v45, v19, v18
	v_add_f32_e32 v45, v170, v45
	v_add_f32_e32 v45, v171, v45
	v_pk_mul_f32 v[18:19], v[212:213], v[212:213]
	v_pk_mul_f32 v[170:171], v[214:215], v[214:215]
	v_add_f32_e32 v46, v19, v18
	v_add_f32_e32 v46, v170, v46
	v_add_f32_e32 v46, v171, v46
	v_pk_mul_f32 v[18:19], v[234:235], v[234:235]
	v_pk_mul_f32 v[170:171], v[236:237], v[236:237]
	v_add_f32_e32 v47, v19, v18
	v_add_f32_e32 v47, v170, v47
	v_add_f32_e32 v47, v171, v47
	v_add_f32_e32 v160, v44, v45
	v_add_f32_e32 v160, v160, v46
	v_add_f32_e32 v160, v160, v47
	v_pk_mul_f32 v[18:19], v[238:239], v[238:239]
	v_pk_mul_f32 v[170:171], v[240:241], v[240:241]
	v_add_f32_e32 v44, v19, v18
	v_add_f32_e32 v44, v170, v44
	v_add_f32_e32 v44, v171, v44
	v_pk_mul_f32 v[18:19], v[242:243], v[242:243]
	v_pk_mul_f32 v[170:171], v[244:245], v[244:245]
	v_add_f32_e32 v45, v19, v18
	v_add_f32_e32 v45, v170, v45
	v_add_f32_e32 v45, v171, v45
	v_pk_mul_f32 v[18:19], v[246:247], v[246:247]
	v_pk_mul_f32 v[170:171], v[248:249], v[248:249]
	v_add_f32_e32 v46, v19, v18
	v_add_f32_e32 v46, v170, v46
	v_add_f32_e32 v46, v171, v46
	v_pk_mul_f32 v[18:19], v[250:251], v[250:251]
	v_pk_mul_f32 v[170:171], v[252:253], v[252:253]
	v_add_f32_e32 v47, v19, v18
	v_add_f32_e32 v47, v170, v47
	v_add_f32_e32 v47, v171, v47
	v_add_f32_e32 v162, v44, v45
	v_add_f32_e32 v162, v162, v46
	v_add_f32_e32 v162, v162, v47
	v_pk_mul_f32 v[18:19], v[128:129], v[128:129]
	v_pk_mul_f32 v[170:171], v[130:131], v[130:131]
	v_add_f32_e32 v44, v19, v18
	v_add_f32_e32 v44, v170, v44
	v_add_f32_e32 v44, v171, v44
	v_pk_mul_f32 v[18:19], v[132:133], v[132:133]
	v_pk_mul_f32 v[170:171], v[134:135], v[134:135]
	v_add_f32_e32 v45, v19, v18
	v_add_f32_e32 v45, v170, v45
	v_add_f32_e32 v45, v171, v45
	v_pk_mul_f32 v[18:19], v[136:137], v[136:137]
	v_pk_mul_f32 v[170:171], v[138:139], v[138:139]
	v_add_f32_e32 v46, v19, v18
	v_add_f32_e32 v46, v170, v46
	v_add_f32_e32 v46, v171, v46
	v_pk_mul_f32 v[18:19], v[142:143], v[142:143]
	v_pk_mul_f32 v[170:171], v[144:145], v[144:145]
	v_add_f32_e32 v47, v19, v18
	v_add_f32_e32 v47, v170, v47
	v_add_f32_e32 v47, v171, v47
	v_add_f32_e32 v164, v44, v45
	v_add_f32_e32 v164, v164, v46
	v_add_f32_e32 v164, v164, v47
	ds_bpermute_b32 v166, v23, v158
	ds_bpermute_b32 v167, v23, v160
	ds_bpermute_b32 v168, v23, v162
	ds_bpermute_b32 v169, v23, v164
	s_waitcnt lgkmcnt(3)
	v_add_f32_e32 v158, v158, v166
	s_waitcnt lgkmcnt(2)
	v_add_f32_e32 v160, v160, v167
	s_waitcnt lgkmcnt(1)
	v_add_f32_e32 v162, v162, v168
	s_waitcnt lgkmcnt(0)
	v_add_f32_e32 v164, v164, v169
	ds_bpermute_b32 v166, v37, v158
	ds_bpermute_b32 v167, v37, v160
	ds_bpermute_b32 v168, v37, v162
	ds_bpermute_b32 v169, v37, v164
	s_waitcnt lgkmcnt(3)
	v_add_f32_e32 v158, v158, v166
	s_waitcnt lgkmcnt(2)
	v_add_f32_e32 v160, v160, v167
	s_waitcnt lgkmcnt(1)
	v_add_f32_e32 v162, v162, v168
	s_waitcnt lgkmcnt(0)
	v_add_f32_e32 v164, v164, v169
	ds_bpermute_b32 v166, v48, v158
	ds_bpermute_b32 v167, v48, v160
	ds_bpermute_b32 v168, v48, v162
	ds_bpermute_b32 v169, v48, v164
	s_waitcnt lgkmcnt(3)
	v_add_f32_e32 v158, v158, v166
	s_waitcnt lgkmcnt(2)
	v_add_f32_e32 v160, v160, v167
	s_waitcnt lgkmcnt(1)
	v_add_f32_e32 v162, v162, v168
	s_waitcnt lgkmcnt(0)
	v_add_f32_e32 v164, v164, v169
	ds_bpermute_b32 v166, v49, v158
	ds_bpermute_b32 v167, v49, v160
	ds_bpermute_b32 v168, v49, v162
	ds_bpermute_b32 v169, v49, v164
	s_waitcnt lgkmcnt(3)
	v_add_f32_e32 v158, v158, v166
	s_waitcnt lgkmcnt(2)
	v_add_f32_e32 v160, v160, v167
	s_waitcnt lgkmcnt(1)
	v_add_f32_e32 v162, v162, v168
	s_waitcnt lgkmcnt(0)
	v_add_f32_e32 v164, v164, v169
	ds_bpermute_b32 v166, v50, v158
	ds_bpermute_b32 v167, v50, v160
	ds_bpermute_b32 v168, v50, v162
	ds_bpermute_b32 v169, v50, v164
	s_waitcnt lgkmcnt(3)
	v_add_f32_e32 v158, v158, v166
	s_waitcnt lgkmcnt(2)
	v_add_f32_e32 v160, v160, v167
	s_waitcnt lgkmcnt(1)
	v_add_f32_e32 v162, v162, v168
	s_waitcnt lgkmcnt(0)
	v_add_f32_e32 v164, v164, v169
	ds_bpermute_b32 v166, v51, v158
	ds_bpermute_b32 v167, v51, v160
	ds_bpermute_b32 v168, v51, v162
	ds_bpermute_b32 v169, v51, v164
	s_waitcnt lgkmcnt(3)
	v_add_f32_e32 v158, v158, v166
	s_waitcnt lgkmcnt(2)
	v_add_f32_e32 v160, v160, v167
	s_waitcnt lgkmcnt(1)
	v_add_f32_e32 v162, v162, v168
	s_waitcnt lgkmcnt(0)
	v_add_f32_e32 v164, v164, v169
	v_pk_add_f32 v[112:113], v[112:113], 1.0 op_sel_hi:[1,0]
	v_pk_add_f32 v[114:115], v[114:115], 1.0 op_sel_hi:[1,0]
	v_pk_add_f32 v[116:117], v[116:117], 1.0 op_sel_hi:[1,0]
	v_pk_add_f32 v[118:119], v[118:119], 1.0 op_sel_hi:[1,0]
	v_pk_add_f32 v[120:121], v[120:121], 1.0 op_sel_hi:[1,0]
	v_pk_add_f32 v[122:123], v[122:123], 1.0 op_sel_hi:[1,0]
	v_pk_add_f32 v[124:125], v[124:125], 1.0 op_sel_hi:[1,0]
	v_pk_add_f32 v[126:127], v[126:127], 1.0 op_sel_hi:[1,0]
	v_fmamk_f32 v158, v158, 0x3a800000, v218
	v_mul_f32_e32 v170, 0x4b800000, v158
	v_cmp_gt_f32_e32 vcc, s71, v158
	s_nop 1
	v_cndmask_b32_e32 v158, v158, v170, vcc
	v_rsq_f32_e32 v158, v158
	s_nop 0
	v_mul_f32_e32 v170, 0x45800000, v158
	v_cndmask_b32_e32 v158, v158, v170, vcc
	v_fmamk_f32 v160, v160, 0x3a800000, v218
	v_mul_f32_e32 v170, 0x4b800000, v160
	v_cmp_gt_f32_e32 vcc, s71, v160
	s_nop 1
	v_cndmask_b32_e32 v160, v160, v170, vcc
	v_rsq_f32_e32 v160, v160
	s_nop 0
	v_mul_f32_e32 v170, 0x45800000, v160
	v_cndmask_b32_e32 v160, v160, v170, vcc
	v_fmamk_f32 v162, v162, 0x3a800000, v218
	v_mul_f32_e32 v170, 0x4b800000, v162
	v_cmp_gt_f32_e32 vcc, s71, v162
	s_nop 1
	v_cndmask_b32_e32 v162, v162, v170, vcc
	v_rsq_f32_e32 v162, v162
	s_nop 0
	v_mul_f32_e32 v170, 0x45800000, v162
	v_cndmask_b32_e32 v162, v162, v170, vcc
	v_fmamk_f32 v164, v164, 0x3a800000, v218
	v_mul_f32_e32 v170, 0x4b800000, v164
	v_cmp_gt_f32_e32 vcc, s71, v164
	s_nop 1
	v_cndmask_b32_e32 v164, v164, v170, vcc
	v_rsq_f32_e32 v164, v164
	s_nop 0
	v_mul_f32_e32 v170, 0x45800000, v164
	v_cndmask_b32_e32 v164, v164, v170, vcc
	s_mov_b64 s[18:19], 0x800
	v_lshlrev_b64 v[16:17], 11, v[42:43]
	v_lshl_add_u64 v[16:17], v[30:31], 0, v[16:17]
	v_pk_mul_f32 v[188:189], v[188:189], v[158:159] op_sel_hi:[1,0]
	v_pk_mul_f32 v[188:189], v[80:81], v[188:189]
	v_pk_fma_f32 v[188:189], v[112:113], v[188:189], v[96:97]
	v_pk_mul_f32 v[190:191], v[190:191], v[158:159] op_sel_hi:[1,0]
	v_pk_mul_f32 v[190:191], v[82:83], v[190:191]
	v_pk_fma_f32 v[190:191], v[114:115], v[190:191], v[98:99]
	v_cvt_pk_bf16_f32 v188, v188, v189
	v_cvt_pk_bf16_f32 v189, v190, v191
	global_store_dwordx2 v[16:17], v[188:189], off
	v_pk_mul_f32 v[192:193], v[192:193], v[158:159] op_sel_hi:[1,0]
	v_pk_mul_f32 v[192:193], v[84:85], v[192:193]
	v_pk_fma_f32 v[192:193], v[116:117], v[192:193], v[100:101]
	v_pk_mul_f32 v[194:195], v[194:195], v[158:159] op_sel_hi:[1,0]
	v_pk_mul_f32 v[194:195], v[86:87], v[194:195]
	v_pk_fma_f32 v[194:195], v[118:119], v[194:195], v[102:103]
	v_cvt_pk_bf16_f32 v192, v192, v193
	v_cvt_pk_bf16_f32 v193, v194, v195
	global_store_dwordx2 v[16:17], v[192:193], off offset:512
	v_pk_mul_f32 v[196:197], v[196:197], v[158:159] op_sel_hi:[1,0]
	v_pk_mul_f32 v[196:197], v[88:89], v[196:197]
	v_pk_fma_f32 v[196:197], v[120:121], v[196:197], v[104:105]
	v_pk_mul_f32 v[198:199], v[198:199], v[158:159] op_sel_hi:[1,0]
	v_pk_mul_f32 v[198:199], v[90:91], v[198:199]
	v_pk_fma_f32 v[198:199], v[122:123], v[198:199], v[106:107]
	v_cvt_pk_bf16_f32 v196, v196, v197
	v_cvt_pk_bf16_f32 v197, v198, v199
	global_store_dwordx2 v[16:17], v[196:197], off offset:1024
	v_pk_mul_f32 v[200:201], v[200:201], v[158:159] op_sel_hi:[1,0]
	v_pk_mul_f32 v[200:201], v[92:93], v[200:201]
	v_pk_fma_f32 v[200:201], v[124:125], v[200:201], v[108:109]
	v_pk_mul_f32 v[202:203], v[202:203], v[158:159] op_sel_hi:[1,0]
	v_pk_mul_f32 v[202:203], v[94:95], v[202:203]
	v_pk_fma_f32 v[202:203], v[126:127], v[202:203], v[110:111]
	v_cvt_pk_bf16_f32 v200, v200, v201
	v_cvt_pk_bf16_f32 v201, v202, v203
	global_store_dwordx2 v[16:17], v[200:201], off offset:1536
	v_lshl_add_u64 v[16:17], v[16:17], 0, s[18:19]
	v_pk_mul_f32 v[204:205], v[204:205], v[160:161] op_sel_hi:[1,0]
	v_pk_mul_f32 v[204:205], v[80:81], v[204:205]
	v_pk_fma_f32 v[204:205], v[112:113], v[204:205], v[96:97]
	v_pk_mul_f32 v[206:207], v[206:207], v[160:161] op_sel_hi:[1,0]
	v_pk_mul_f32 v[206:207], v[82:83], v[206:207]
	v_pk_fma_f32 v[206:207], v[114:115], v[206:207], v[98:99]
	v_cvt_pk_bf16_f32 v204, v204, v205
	v_cvt_pk_bf16_f32 v205, v206, v207
	global_store_dwordx2 v[16:17], v[204:205], off
	v_pk_mul_f32 v[208:209], v[208:209], v[160:161] op_sel_hi:[1,0]
	v_pk_mul_f32 v[208:209], v[84:85], v[208:209]
	v_pk_fma_f32 v[208:209], v[116:117], v[208:209], v[100:101]
	v_pk_mul_f32 v[210:211], v[210:211], v[160:161] op_sel_hi:[1,0]
	v_pk_mul_f32 v[210:211], v[86:87], v[210:211]
	v_pk_fma_f32 v[210:211], v[118:119], v[210:211], v[102:103]
	v_cvt_pk_bf16_f32 v208, v208, v209
	v_cvt_pk_bf16_f32 v209, v210, v211
	global_store_dwordx2 v[16:17], v[208:209], off offset:512
	v_pk_mul_f32 v[212:213], v[212:213], v[160:161] op_sel_hi:[1,0]
	v_pk_mul_f32 v[212:213], v[88:89], v[212:213]
	v_pk_fma_f32 v[212:213], v[120:121], v[212:213], v[104:105]
	v_pk_mul_f32 v[214:215], v[214:215], v[160:161] op_sel_hi:[1,0]
	v_pk_mul_f32 v[214:215], v[90:91], v[214:215]
	v_pk_fma_f32 v[214:215], v[122:123], v[214:215], v[106:107]
	v_cvt_pk_bf16_f32 v212, v212, v213
	v_cvt_pk_bf16_f32 v213, v214, v215
	global_store_dwordx2 v[16:17], v[212:213], off offset:1024
	v_pk_mul_f32 v[234:235], v[234:235], v[160:161] op_sel_hi:[1,0]
	v_pk_mul_f32 v[234:235], v[92:93], v[234:235]
	v_pk_fma_f32 v[234:235], v[124:125], v[234:235], v[108:109]
	v_pk_mul_f32 v[236:237], v[236:237], v[160:161] op_sel_hi:[1,0]
	v_pk_mul_f32 v[236:237], v[94:95], v[236:237]
	v_pk_fma_f32 v[236:237], v[126:127], v[236:237], v[110:111]
	v_cvt_pk_bf16_f32 v234, v234, v235
	v_cvt_pk_bf16_f32 v235, v236, v237
	global_store_dwordx2 v[16:17], v[234:235], off offset:1536
	v_lshl_add_u64 v[16:17], v[16:17], 0, s[18:19]
	v_pk_mul_f32 v[238:239], v[238:239], v[162:163] op_sel_hi:[1,0]
	v_pk_mul_f32 v[238:239], v[80:81], v[238:239]
	v_pk_fma_f32 v[238:239], v[112:113], v[238:239], v[96:97]
	v_pk_mul_f32 v[240:241], v[240:241], v[162:163] op_sel_hi:[1,0]
	v_pk_mul_f32 v[240:241], v[82:83], v[240:241]
	v_pk_fma_f32 v[240:241], v[114:115], v[240:241], v[98:99]
	v_cvt_pk_bf16_f32 v238, v238, v239
	v_cvt_pk_bf16_f32 v239, v240, v241
	global_store_dwordx2 v[16:17], v[238:239], off
	v_pk_mul_f32 v[242:243], v[242:243], v[162:163] op_sel_hi:[1,0]
	v_pk_mul_f32 v[242:243], v[84:85], v[242:243]
	v_pk_fma_f32 v[242:243], v[116:117], v[242:243], v[100:101]
	v_pk_mul_f32 v[244:245], v[244:245], v[162:163] op_sel_hi:[1,0]
	v_pk_mul_f32 v[244:245], v[86:87], v[244:245]
	v_pk_fma_f32 v[244:245], v[118:119], v[244:245], v[102:103]
	v_cvt_pk_bf16_f32 v242, v242, v243
	v_cvt_pk_bf16_f32 v243, v244, v245
	global_store_dwordx2 v[16:17], v[242:243], off offset:512
	v_pk_mul_f32 v[246:247], v[246:247], v[162:163] op_sel_hi:[1,0]
	v_pk_mul_f32 v[246:247], v[88:89], v[246:247]
	v_pk_fma_f32 v[246:247], v[120:121], v[246:247], v[104:105]
	v_pk_mul_f32 v[248:249], v[248:249], v[162:163] op_sel_hi:[1,0]
	v_pk_mul_f32 v[248:249], v[90:91], v[248:249]
	v_pk_fma_f32 v[248:249], v[122:123], v[248:249], v[106:107]
	v_cvt_pk_bf16_f32 v246, v246, v247
	v_cvt_pk_bf16_f32 v247, v248, v249
	global_store_dwordx2 v[16:17], v[246:247], off offset:1024
	v_pk_mul_f32 v[250:251], v[250:251], v[162:163] op_sel_hi:[1,0]
	v_pk_mul_f32 v[250:251], v[92:93], v[250:251]
	v_pk_fma_f32 v[250:251], v[124:125], v[250:251], v[108:109]
	v_pk_mul_f32 v[252:253], v[252:253], v[162:163] op_sel_hi:[1,0]
	v_pk_mul_f32 v[252:253], v[94:95], v[252:253]
	v_pk_fma_f32 v[252:253], v[126:127], v[252:253], v[110:111]
	v_cvt_pk_bf16_f32 v250, v250, v251
	v_cvt_pk_bf16_f32 v251, v252, v253
	global_store_dwordx2 v[16:17], v[250:251], off offset:1536
	v_lshl_add_u64 v[16:17], v[16:17], 0, s[18:19]
	v_pk_mul_f32 v[128:129], v[128:129], v[164:165] op_sel_hi:[1,0]
	v_pk_mul_f32 v[128:129], v[80:81], v[128:129]
	v_pk_fma_f32 v[128:129], v[112:113], v[128:129], v[96:97]
	v_pk_mul_f32 v[130:131], v[130:131], v[164:165] op_sel_hi:[1,0]
	v_pk_mul_f32 v[130:131], v[82:83], v[130:131]
	v_pk_fma_f32 v[130:131], v[114:115], v[130:131], v[98:99]
	v_cvt_pk_bf16_f32 v128, v128, v129
	v_cvt_pk_bf16_f32 v129, v130, v131
	global_store_dwordx2 v[16:17], v[128:129], off
	v_pk_mul_f32 v[132:133], v[132:133], v[164:165] op_sel_hi:[1,0]
	v_pk_mul_f32 v[132:133], v[84:85], v[132:133]
	v_pk_fma_f32 v[132:133], v[116:117], v[132:133], v[100:101]
	v_pk_mul_f32 v[134:135], v[134:135], v[164:165] op_sel_hi:[1,0]
	v_pk_mul_f32 v[134:135], v[86:87], v[134:135]
	v_pk_fma_f32 v[134:135], v[118:119], v[134:135], v[102:103]
	v_cvt_pk_bf16_f32 v132, v132, v133
	v_cvt_pk_bf16_f32 v133, v134, v135
	global_store_dwordx2 v[16:17], v[132:133], off offset:512
	v_pk_mul_f32 v[136:137], v[136:137], v[164:165] op_sel_hi:[1,0]
	v_pk_mul_f32 v[136:137], v[88:89], v[136:137]
	v_pk_fma_f32 v[136:137], v[120:121], v[136:137], v[104:105]
	v_pk_mul_f32 v[138:139], v[138:139], v[164:165] op_sel_hi:[1,0]
	v_pk_mul_f32 v[138:139], v[90:91], v[138:139]
	v_pk_fma_f32 v[138:139], v[122:123], v[138:139], v[106:107]
	v_cvt_pk_bf16_f32 v136, v136, v137
	v_cvt_pk_bf16_f32 v137, v138, v139
	global_store_dwordx2 v[16:17], v[136:137], off offset:1024
	v_pk_mul_f32 v[142:143], v[142:143], v[164:165] op_sel_hi:[1,0]
	v_pk_mul_f32 v[142:143], v[92:93], v[142:143]
	v_pk_fma_f32 v[142:143], v[124:125], v[142:143], v[108:109]
	v_pk_mul_f32 v[144:145], v[144:145], v[164:165] op_sel_hi:[1,0]
	v_pk_mul_f32 v[144:145], v[94:95], v[144:145]
	v_pk_fma_f32 v[144:145], v[126:127], v[144:145], v[110:111]
	v_cvt_pk_bf16_f32 v142, v142, v143
	v_cvt_pk_bf16_f32 v143, v144, v145
	global_store_dwordx2 v[16:17], v[142:143], off offset:1536
	s_branch .LBB0_869
